# mixer residual epilogue: block-start waits (store acks of the previous row group) removed, the next group's loads overlap the previous group's stores; on top of v50
# baseline (speedup 1.0000x reference)
.LBB0_1057:
	v_ashrrev_i32_e32 v199, 31, v198
	global_load_dwordx4 v[218:221], v[186:187], off
	global_load_dwordx4 v[222:225], v[186:187], off offset:16
	v_lshlrev_b64 v[154:155], 12, v[198:199]
	v_ashrrev_i32_e32 v201, 31, v200
	v_lshl_add_u64 v[154:155], v[226:227], 0, v[154:155]
	v_ashrrev_i32_e32 v195, 31, v194
	v_lshlrev_b64 v[150:151], 12, v[200:201]
	flat_load_dwordx4 v[158:161], v[154:155]
	v_lshlrev_b64 v[154:155], 12, v[194:195]
	v_lshl_add_u64 v[146:147], v[226:227], 0, v[214:215]
	v_lshl_add_u64 v[150:151], v[226:227], 0, v[150:151]
	v_lshl_add_u64 v[154:155], v[226:227], 0, v[154:155]
	flat_load_dwordx4 v[146:149], v[146:147]
	flat_load_dwordx4 v[150:153], v[150:151]
	flat_load_dwordx4 v[182:185], v[154:155]
	s_waitcnt vmcnt(0) lgkmcnt(0)
	v_lshlrev_b32_e32 v156, 16, v159
	v_and_b32_e32 v157, 0xffff0000, v159
	v_lshlrev_b32_e32 v154, 16, v158
	v_lshlrev_b32_e32 v170, 16, v146
	v_and_b32_e32 v171, 0xffff0000, v146
	v_lshlrev_b32_e32 v172, 16, v147
	v_and_b32_e32 v173, 0xffff0000, v147
	v_lshlrev_b32_e32 v174, 16, v148
	v_and_b32_e32 v175, 0xffff0000, v148
	v_lshlrev_b32_e32 v176, 16, v149
	v_and_b32_e32 v177, 0xffff0000, v149
	v_and_b32_e32 v155, 0xffff0000, v158
	v_lshlrev_b32_e32 v158, 16, v160
	v_and_b32_e32 v159, 0xffff0000, v160
	v_lshlrev_b32_e32 v160, 16, v161
	v_and_b32_e32 v161, 0xffff0000, v161
	s_waitcnt vmcnt(0) lgkmcnt(0)
	v_lshlrev_b32_e32 v162, 16, v150
	v_and_b32_e32 v163, 0xffff0000, v150
	v_lshlrev_b32_e32 v164, 16, v151
	v_and_b32_e32 v165, 0xffff0000, v151
	v_lshlrev_b32_e32 v166, 16, v152
	v_and_b32_e32 v167, 0xffff0000, v152
	v_lshlrev_b32_e32 v168, 16, v153
	v_and_b32_e32 v169, 0xffff0000, v153
	v_lshlrev_b32_e32 v146, 16, v182
	v_and_b32_e32 v147, 0xffff0000, v182
	v_lshlrev_b32_e32 v148, 16, v183
	v_and_b32_e32 v149, 0xffff0000, v183
	v_lshlrev_b32_e32 v150, 16, v184
	v_and_b32_e32 v151, 0xffff0000, v184
	v_lshlrev_b32_e32 v152, 16, v185
	v_and_b32_e32 v153, 0xffff0000, v185
	s_cmp_lt_u32 s68, 2
	s_cbranch_scc1 .Lxr2_0
	v_rcp_f32_e32 v218, v218
	v_rcp_f32_e32 v219, v219
	v_rcp_f32_e32 v220, v220
	v_rcp_f32_e32 v221, v221
	v_rcp_f32_e32 v222, v222
	v_rcp_f32_e32 v223, v223
	v_rcp_f32_e32 v224, v224
	v_rcp_f32_e32 v225, v225
	s_nop 0
	v_pk_mul_f32 v[146:147], v[146:147], v[218:219]
	v_pk_mul_f32 v[148:149], v[148:149], v[220:221]
	v_pk_mul_f32 v[150:151], v[150:151], v[222:223]
	v_pk_mul_f32 v[152:153], v[152:153], v[224:225]
	v_pk_mul_f32 v[154:155], v[154:155], v[218:219]
	v_pk_mul_f32 v[156:157], v[156:157], v[220:221]
	v_pk_mul_f32 v[158:159], v[158:159], v[222:223]
	v_pk_mul_f32 v[160:161], v[160:161], v[224:225]
	v_pk_mul_f32 v[162:163], v[162:163], v[218:219]
	v_pk_mul_f32 v[164:165], v[164:165], v[220:221]
	v_pk_mul_f32 v[166:167], v[166:167], v[222:223]
	v_pk_mul_f32 v[168:169], v[168:169], v[224:225]
	v_pk_mul_f32 v[170:171], v[170:171], v[218:219]
	v_pk_mul_f32 v[172:173], v[172:173], v[220:221]
	v_pk_mul_f32 v[174:175], v[174:175], v[222:223]
	v_pk_mul_f32 v[176:177], v[176:177], v[224:225]

.LBB0_1060:
	v_ashrrev_i32_e32 v205, 31, v204
	global_load_dwordx4 v[228:231], v[186:187], off
	global_load_dwordx2 v[234:235], v[186:187], off offset:16
	global_load_dwordx2 v[246:247], v[186:187], off offset:24
	v_lshlrev_b64 v[122:123], 12, v[204:205]
	v_ashrrev_i32_e32 v207, 31, v206
	v_lshl_add_u64 v[122:123], v[226:227], 0, v[122:123]
	v_ashrrev_i32_e32 v203, 31, v202
	v_lshlrev_b64 v[118:119], 12, v[206:207]
	flat_load_dwordx4 v[126:129], v[122:123]
	v_lshlrev_b64 v[122:123], 12, v[202:203]
	v_lshl_add_u64 v[114:115], v[226:227], 0, v[232:233]
	v_lshl_add_u64 v[118:119], v[226:227], 0, v[118:119]
	v_lshl_add_u64 v[122:123], v[226:227], 0, v[122:123]
	flat_load_dwordx4 v[114:117], v[114:115]
	flat_load_dwordx4 v[118:121], v[118:119]
	flat_load_dwordx4 v[182:185], v[122:123]
	s_waitcnt vmcnt(0) lgkmcnt(0)
	v_lshlrev_b32_e32 v124, 16, v127
	v_and_b32_e32 v125, 0xffff0000, v127
	v_lshlrev_b32_e32 v122, 16, v126
	v_lshlrev_b32_e32 v138, 16, v114
	v_and_b32_e32 v139, 0xffff0000, v114
	v_lshlrev_b32_e32 v140, 16, v115
	v_and_b32_e32 v141, 0xffff0000, v115
	v_lshlrev_b32_e32 v142, 16, v116
	v_and_b32_e32 v143, 0xffff0000, v116
	v_lshlrev_b32_e32 v144, 16, v117
	v_and_b32_e32 v145, 0xffff0000, v117
	v_and_b32_e32 v123, 0xffff0000, v126
	v_lshlrev_b32_e32 v126, 16, v128
	v_and_b32_e32 v127, 0xffff0000, v128
	v_lshlrev_b32_e32 v128, 16, v129
	v_and_b32_e32 v129, 0xffff0000, v129
	s_waitcnt vmcnt(0) lgkmcnt(0)
	v_lshlrev_b32_e32 v130, 16, v118
	v_and_b32_e32 v131, 0xffff0000, v118
	v_lshlrev_b32_e32 v132, 16, v119
	v_and_b32_e32 v133, 0xffff0000, v119
	v_lshlrev_b32_e32 v134, 16, v120
	v_and_b32_e32 v135, 0xffff0000, v120
	v_lshlrev_b32_e32 v136, 16, v121
	v_and_b32_e32 v137, 0xffff0000, v121
	v_lshlrev_b32_e32 v114, 16, v182
	v_and_b32_e32 v115, 0xffff0000, v182
	v_lshlrev_b32_e32 v116, 16, v183
	v_and_b32_e32 v117, 0xffff0000, v183
	v_lshlrev_b32_e32 v118, 16, v184
	v_and_b32_e32 v119, 0xffff0000, v184
	v_lshlrev_b32_e32 v120, 16, v185
	v_and_b32_e32 v121, 0xffff0000, v185
	s_cmp_lt_u32 s68, 2
	s_cbranch_scc1 .Lxr2_1
	v_rcp_f32_e32 v228, v228
	v_rcp_f32_e32 v229, v229
	v_rcp_f32_e32 v230, v230
	v_rcp_f32_e32 v231, v231
	v_rcp_f32_e32 v234, v234
	v_rcp_f32_e32 v235, v235
	v_rcp_f32_e32 v246, v246
	v_rcp_f32_e32 v247, v247
	s_nop 0
	v_pk_mul_f32 v[114:115], v[114:115], v[228:229]
	v_pk_mul_f32 v[116:117], v[116:117], v[230:231]
	v_pk_mul_f32 v[118:119], v[118:119], v[234:235]
	v_pk_mul_f32 v[120:121], v[120:121], v[246:247]
	v_pk_mul_f32 v[122:123], v[122:123], v[228:229]
	v_pk_mul_f32 v[124:125], v[124:125], v[230:231]
	v_pk_mul_f32 v[126:127], v[126:127], v[234:235]
	v_pk_mul_f32 v[128:129], v[128:129], v[246:247]
	v_pk_mul_f32 v[130:131], v[130:131], v[228:229]
	v_pk_mul_f32 v[132:133], v[132:133], v[230:231]
	v_pk_mul_f32 v[134:135], v[134:135], v[234:235]
	v_pk_mul_f32 v[136:137], v[136:137], v[246:247]
	v_pk_mul_f32 v[138:139], v[138:139], v[228:229]
	v_pk_mul_f32 v[140:141], v[140:141], v[230:231]
	v_pk_mul_f32 v[142:143], v[142:143], v[234:235]
	v_pk_mul_f32 v[144:145], v[144:145], v[246:247]

.LBB0_1068:
	v_or_b32_e32 v120, 0x80, v196
	v_ashrrev_i32_e32 v121, 31, v120
	s_andn2_b64 vcc, exec, s[30:31]
	v_lshlrev_b64 v[196:197], 1, v[120:121]
	s_cbranch_vccnz .LBB0_1070
	global_load_dwordx4 v[208:211], v[186:187], off offset:512
	global_load_dwordx2 v[212:213], v[186:187], off offset:528
	global_load_dwordx2 v[234:235], v[186:187], off offset:536
	v_lshlrev_b64 v[90:91], 12, v[198:199]
	v_lshl_add_u64 v[90:91], s[12:13], 0, v[90:91]
	v_lshl_add_u64 v[90:91], v[90:91], 0, v[196:197]
	v_lshlrev_b64 v[86:87], 12, v[200:201]
	flat_load_dwordx4 v[94:97], v[90:91]
	v_lshlrev_b64 v[90:91], 12, v[194:195]
	v_lshl_add_u64 v[82:83], s[12:13], 0, v[214:215]
	v_lshl_add_u64 v[86:87], s[12:13], 0, v[86:87]
	v_lshl_add_u64 v[90:91], s[12:13], 0, v[90:91]
	v_lshl_add_u64 v[82:83], v[82:83], 0, v[196:197]
	v_lshl_add_u64 v[86:87], v[86:87], 0, v[196:197]
	v_lshl_add_u64 v[90:91], v[90:91], 0, v[196:197]
	flat_load_dwordx4 v[82:85], v[82:83]
	flat_load_dwordx4 v[86:89], v[86:87]
	flat_load_dwordx4 v[182:185], v[90:91]
	s_waitcnt vmcnt(0) lgkmcnt(0)
	v_lshlrev_b32_e32 v92, 16, v95
	v_and_b32_e32 v93, 0xffff0000, v95
	v_lshlrev_b32_e32 v90, 16, v94
	v_and_b32_e32 v91, 0xffff0000, v94
	v_lshlrev_b32_e32 v94, 16, v96
	v_and_b32_e32 v95, 0xffff0000, v96
	v_lshlrev_b32_e32 v106, 16, v82
	v_and_b32_e32 v107, 0xffff0000, v82
	v_lshlrev_b32_e32 v108, 16, v83
	v_and_b32_e32 v109, 0xffff0000, v83
	v_lshlrev_b32_e32 v110, 16, v84
	v_and_b32_e32 v111, 0xffff0000, v84
	v_lshlrev_b32_e32 v112, 16, v85
	v_and_b32_e32 v113, 0xffff0000, v85
	v_lshlrev_b32_e32 v96, 16, v97
	v_and_b32_e32 v97, 0xffff0000, v97
	s_waitcnt vmcnt(0) lgkmcnt(0)
	v_lshlrev_b32_e32 v98, 16, v86
	v_and_b32_e32 v99, 0xffff0000, v86
	v_lshlrev_b32_e32 v100, 16, v87
	v_and_b32_e32 v101, 0xffff0000, v87
	v_lshlrev_b32_e32 v102, 16, v88
	v_and_b32_e32 v103, 0xffff0000, v88
	v_lshlrev_b32_e32 v104, 16, v89
	v_and_b32_e32 v105, 0xffff0000, v89
	v_lshlrev_b32_e32 v82, 16, v182
	v_and_b32_e32 v83, 0xffff0000, v182
	v_lshlrev_b32_e32 v84, 16, v183
	v_and_b32_e32 v85, 0xffff0000, v183
	v_lshlrev_b32_e32 v86, 16, v184
	v_and_b32_e32 v87, 0xffff0000, v184
	v_lshlrev_b32_e32 v88, 16, v185
	v_and_b32_e32 v89, 0xffff0000, v185
	s_cmp_lt_u32 s68, 2
	s_cbranch_scc1 .Lxr2_2
	v_rcp_f32_e32 v208, v208
	v_rcp_f32_e32 v209, v209
	v_rcp_f32_e32 v210, v210
	v_rcp_f32_e32 v211, v211
	v_rcp_f32_e32 v212, v212
	v_rcp_f32_e32 v213, v213
	v_rcp_f32_e32 v234, v234
	v_rcp_f32_e32 v235, v235
	s_nop 0
	v_pk_mul_f32 v[82:83], v[82:83], v[208:209]
	v_pk_mul_f32 v[84:85], v[84:85], v[210:211]
	v_pk_mul_f32 v[86:87], v[86:87], v[212:213]
	v_pk_mul_f32 v[88:89], v[88:89], v[234:235]
	v_pk_mul_f32 v[90:91], v[90:91], v[208:209]
	v_pk_mul_f32 v[92:93], v[92:93], v[210:211]
	v_pk_mul_f32 v[94:95], v[94:95], v[212:213]
	v_pk_mul_f32 v[96:97], v[96:97], v[234:235]
	v_pk_mul_f32 v[98:99], v[98:99], v[208:209]
	v_pk_mul_f32 v[100:101], v[100:101], v[210:211]
	v_pk_mul_f32 v[102:103], v[102:103], v[212:213]
	v_pk_mul_f32 v[104:105], v[104:105], v[234:235]
	v_pk_mul_f32 v[106:107], v[106:107], v[208:209]
	v_pk_mul_f32 v[108:109], v[108:109], v[210:211]
	v_pk_mul_f32 v[110:111], v[110:111], v[212:213]
	v_pk_mul_f32 v[112:113], v[112:113], v[234:235]

.LBB0_1072:
	global_load_dwordx4 v[208:211], v[186:187], off offset:512
	global_load_dwordx4 v[212:215], v[186:187], off offset:528
	v_lshlrev_b64 v[42:43], 12, v[204:205]
	v_lshl_add_u64 v[42:43], s[12:13], 0, v[42:43]
	v_lshl_add_u64 v[42:43], v[42:43], 0, v[196:197]
	v_lshlrev_b64 v[38:39], 12, v[206:207]
	flat_load_dwordx4 v[46:49], v[42:43]
	v_lshlrev_b64 v[42:43], 12, v[202:203]
	v_lshl_add_u64 v[34:35], s[12:13], 0, v[232:233]
	v_lshl_add_u64 v[38:39], s[12:13], 0, v[38:39]
	v_lshl_add_u64 v[42:43], s[12:13], 0, v[42:43]
	v_lshl_add_u64 v[34:35], v[34:35], 0, v[196:197]
	v_lshl_add_u64 v[38:39], v[38:39], 0, v[196:197]
	v_lshl_add_u64 v[42:43], v[42:43], 0, v[196:197]
	flat_load_dwordx4 v[34:37], v[34:35]
	flat_load_dwordx4 v[38:41], v[38:39]
	flat_load_dwordx4 v[182:185], v[42:43]
	s_waitcnt vmcnt(0) lgkmcnt(0)
	v_lshlrev_b32_e32 v44, 16, v47
	v_and_b32_e32 v45, 0xffff0000, v47
	v_lshlrev_b32_e32 v42, 16, v46
	v_and_b32_e32 v43, 0xffff0000, v46
	v_lshlrev_b32_e32 v46, 16, v48
	v_and_b32_e32 v47, 0xffff0000, v48
	v_lshlrev_b32_e32 v58, 16, v34
	v_and_b32_e32 v59, 0xffff0000, v34
	v_lshlrev_b32_e32 v60, 16, v35
	v_and_b32_e32 v61, 0xffff0000, v35
	v_lshlrev_b32_e32 v62, 16, v36
	v_and_b32_e32 v63, 0xffff0000, v36
	v_lshlrev_b32_e32 v64, 16, v37
	v_and_b32_e32 v65, 0xffff0000, v37
	v_lshlrev_b32_e32 v48, 16, v49
	v_and_b32_e32 v49, 0xffff0000, v49
	s_waitcnt vmcnt(0) lgkmcnt(0)
	v_lshlrev_b32_e32 v50, 16, v38
	v_and_b32_e32 v51, 0xffff0000, v38
	v_lshlrev_b32_e32 v52, 16, v39
	v_and_b32_e32 v53, 0xffff0000, v39
	v_lshlrev_b32_e32 v54, 16, v40
	v_and_b32_e32 v55, 0xffff0000, v40
	v_lshlrev_b32_e32 v56, 16, v41
	v_and_b32_e32 v57, 0xffff0000, v41
	v_lshlrev_b32_e32 v34, 16, v182
	v_and_b32_e32 v35, 0xffff0000, v182
	v_lshlrev_b32_e32 v36, 16, v183
	v_and_b32_e32 v37, 0xffff0000, v183
	v_lshlrev_b32_e32 v38, 16, v184
	v_and_b32_e32 v39, 0xffff0000, v184
	v_lshlrev_b32_e32 v40, 16, v185
	v_and_b32_e32 v41, 0xffff0000, v185
	s_cmp_lt_u32 s68, 2
	s_cbranch_scc1 .Lxr2_3
	v_rcp_f32_e32 v208, v208
	v_rcp_f32_e32 v209, v209
	v_rcp_f32_e32 v210, v210
	v_rcp_f32_e32 v211, v211
	v_rcp_f32_e32 v212, v212
	v_rcp_f32_e32 v213, v213
	v_rcp_f32_e32 v214, v214
	v_rcp_f32_e32 v215, v215
	s_nop 0
	v_pk_mul_f32 v[34:35], v[34:35], v[208:209]
	v_pk_mul_f32 v[36:37], v[36:37], v[210:211]
	v_pk_mul_f32 v[38:39], v[38:39], v[212:213]
	v_pk_mul_f32 v[40:41], v[40:41], v[214:215]
	v_pk_mul_f32 v[42:43], v[42:43], v[208:209]
	v_pk_mul_f32 v[44:45], v[44:45], v[210:211]
	v_pk_mul_f32 v[46:47], v[46:47], v[212:213]
	v_pk_mul_f32 v[48:49], v[48:49], v[214:215]
	v_pk_mul_f32 v[50:51], v[50:51], v[208:209]
	v_pk_mul_f32 v[52:53], v[52:53], v[210:211]
	v_pk_mul_f32 v[54:55], v[54:55], v[212:213]
	v_pk_mul_f32 v[56:57], v[56:57], v[214:215]
	v_pk_mul_f32 v[58:59], v[58:59], v[208:209]
	v_pk_mul_f32 v[60:61], v[60:61], v[210:211]
	v_pk_mul_f32 v[62:63], v[62:63], v[212:213]
	v_pk_mul_f32 v[64:65], v[64:65], v[214:215]
